# FFN gate/up epilogue: packed f32 multiplies/adds (v_pk_mul_f32 / v_pk_add_f32) in the hand-written epilogue math
# speedup vs baseline: 1.0038x; 1.0013x over previous
; __host__ __device__ __forceinline__ size_t tiled_off(int row, int col, int K) { return ((size_t)(row >> 7) * (K >> 6) + (col >> 6)) * 8192 + (lds_byte(row & 127, col & 63) >> 1); }
; __device__ __forceinline__ unsigned cvt_pk_bf16(float lo, float hi) { unsigned r; asm volatile("v_cvt_pk_bf16_f32 %0, %1, %2" : "=v"(r) : "v"(lo), "v"(hi)); return r; }
; __device__ __forceinline__ float fast_sigmoid(float x) { return __builtin_amdgcn_rcpf(1.0f + __builtin_amdgcn_exp2f(x * -1.4426950408889634f)); }
;     __device__ __forceinline__ void operator()(const f32x4 (&acc)[2][2][4][2], const Unit& u, int wr, int wc, int fr, int fq, const PG8_LAS float* rtab) const {
;     ...
;             for (int m = 0; m < 4; ++m) { const float r = rs[ai][m]; float o[8];
; #pragma unroll
;                 for (int n = 0; n < 2; ++n) { const f32x4 a = acc[ai][0][m][n] * r + bv[n], g = acc[ai][1][m][n] * r + bg[n];
; #pragma unroll
;                     for (int e = 0; e < 4; ++e) o[4 * n + e] = (MODE == 0) ? a[e] * fast_sigmoid(g[e]) : a[e] * fast_sigmoid(a[e]) * g[e]; }
;                 u32x4 w; w.x = cvt_pk_bf16(o[0], o[1]); w.y = cvt_pk_bf16(o[2], o[3]); w.z = cvt_pk_bf16(o[4], o[5]); w.w = cvt_pk_bf16(o[6], o[7]);
;                 if (MODE == 1) *(u32x4*)(O + tiled_off(row0 + ai * HALF + m * 16, lcol, ldc)) = w;
.LBB0_793:
	s_lshl_b32 s53, s61, 10
	s_and_b32 s55, s53, 0x400
	v_add_u32_e32 v130, s55, v146
	ds_read2_b32 v[152:153], v130 offset1:16
	ds_read2_b32 v[140:141], v130 offset0:32 offset1:48
	ds_read2_b32 v[138:139], v130 offset0:128 offset1:144
	ds_read2_b32 v[136:137], v130 offset0:160 offset1:176
	s_waitcnt lgkmcnt(0)
	s_lshl_b32 s53, s60, 8
	s_add_i32 s53, s53, s38
	v_or_b32_e32 v151, s53, v142
	v_mul_f32_e32 v224, 0xbfb8aa3b, v152
	v_mul_f32_e32 v225, v152, v152
	v_pk_mul_f32 v[234:235], v[124:125], v[224:225] op_sel_hi:[1,0]
	v_pk_mul_f32 v[236:237], v[126:127], v[224:225] op_sel_hi:[1,0]
	v_pk_mul_f32 v[238:239], v[116:117], v[224:225] op_sel_hi:[1,0]
	v_pk_mul_f32 v[240:241], v[118:119], v[224:225] op_sel_hi:[1,0]
	v_pk_mul_f32 v[226:227], v[124:125], v[120:121]
	v_pk_mul_f32 v[228:229], v[126:127], v[122:123]
	v_pk_mul_f32 v[230:231], v[116:117], v[112:113]
	v_pk_mul_f32 v[232:233], v[118:119], v[114:115]
	v_exp_f32_e32 v234, v234
	v_exp_f32_e32 v235, v235
	v_exp_f32_e32 v236, v236
	v_exp_f32_e32 v237, v237
	v_exp_f32_e32 v238, v238
	v_exp_f32_e32 v239, v239
	v_exp_f32_e32 v240, v240
	v_exp_f32_e32 v241, v241
	v_pk_mul_f32 v[226:227], v[226:227], v[224:225] op_sel:[0,1] op_sel_hi:[1,1]
	v_pk_mul_f32 v[228:229], v[228:229], v[224:225] op_sel:[0,1] op_sel_hi:[1,1]
	v_pk_mul_f32 v[230:231], v[230:231], v[224:225] op_sel:[0,1] op_sel_hi:[1,1]
	v_pk_mul_f32 v[232:233], v[232:233], v[224:225] op_sel:[0,1] op_sel_hi:[1,1]
	v_pk_add_f32 v[234:235], v[234:235], 1.0 op_sel_hi:[1,0]
	v_pk_add_f32 v[236:237], v[236:237], 1.0 op_sel_hi:[1,0]
	v_pk_add_f32 v[238:239], v[238:239], 1.0 op_sel_hi:[1,0]
	v_pk_add_f32 v[240:241], v[240:241], 1.0 op_sel_hi:[1,0]
	v_rcp_f32_e32 v234, v234
	v_rcp_f32_e32 v235, v235
	v_rcp_f32_e32 v236, v236
	v_rcp_f32_e32 v237, v237
	v_rcp_f32_e32 v238, v238
	v_rcp_f32_e32 v239, v239
	v_rcp_f32_e32 v240, v240
	v_rcp_f32_e32 v241, v241
	v_pk_mul_f32 v[226:227], v[226:227], v[234:235]
	v_pk_mul_f32 v[228:229], v[228:229], v[236:237]
	v_pk_mul_f32 v[230:231], v[230:231], v[238:239]
	v_pk_mul_f32 v[232:233], v[232:233], v[240:241]
	v_cvt_pk_bf16_f32 v242, v226, v227
	v_cvt_pk_bf16_f32 v243, v228, v229
	v_cvt_pk_bf16_f32 v244, v230, v231
	v_cvt_pk_bf16_f32 v245, v232, v233
	v_lshlrev_b32_e32 v116, 6, v151
	v_and_or_b32 v118, v116, s40, v143
	v_lshlrev_b32_e32 v116, 2, v151
	v_and_b32_e32 v119, 32, v116
	s_lshl_b32 s55, s68, 7
	s_or_b32 s55, s55, s39
	s_ashr_i32 s60, s55, 6
	s_ashr_i32 s55, s53, 7
	s_mul_i32 s55, s55, 44
	s_ashr_i32 s61, s60, 31
	s_ashr_i32 s69, s55, 31
	s_add_u32 s68, s55, s60
	s_addc_u32 s69, s69, s61
	s_lshl_b64 s[68:69], s[68:69], 14
	s_add_u32 s68, s14, s68
	v_bitop3_b32 v120, v118, s42, v119 bitop3:0xde
	s_addc_u32 s69, s15, s69
	global_store_dwordx4 v120, v[242:245], s[68:69]
	s_or_b32 s55, s53, 16
	s_lshr_b32 s55, s55, 3
	s_and_b32 s55, s55, 10
	s_or_b32 s55, s55, s41
	s_lshl_b32 s55, s55, 10
	v_mul_f32_e32 v224, 0xbfb8aa3b, v140
	v_mul_f32_e32 v225, v140, v140
	v_pk_mul_f32 v[234:235], v[92:93], v[224:225] op_sel_hi:[1,0]
	v_pk_mul_f32 v[236:237], v[94:95], v[224:225] op_sel_hi:[1,0]
	v_pk_mul_f32 v[238:239], v[84:85], v[224:225] op_sel_hi:[1,0]
	v_pk_mul_f32 v[240:241], v[86:87], v[224:225] op_sel_hi:[1,0]
	v_pk_mul_f32 v[226:227], v[92:93], v[88:89]
	v_pk_mul_f32 v[228:229], v[94:95], v[90:91]
	v_pk_mul_f32 v[230:231], v[84:85], v[80:81]
	v_pk_mul_f32 v[232:233], v[86:87], v[82:83]
	v_exp_f32_e32 v234, v234
	v_exp_f32_e32 v235, v235
	v_exp_f32_e32 v236, v236
	v_exp_f32_e32 v237, v237
	v_exp_f32_e32 v238, v238
	v_exp_f32_e32 v239, v239
	v_exp_f32_e32 v240, v240
	v_exp_f32_e32 v241, v241
	v_pk_mul_f32 v[226:227], v[226:227], v[224:225] op_sel:[0,1] op_sel_hi:[1,1]
	v_pk_mul_f32 v[228:229], v[228:229], v[224:225] op_sel:[0,1] op_sel_hi:[1,1]
	v_pk_mul_f32 v[230:231], v[230:231], v[224:225] op_sel:[0,1] op_sel_hi:[1,1]
	v_pk_mul_f32 v[232:233], v[232:233], v[224:225] op_sel:[0,1] op_sel_hi:[1,1]
	v_pk_add_f32 v[234:235], v[234:235], 1.0 op_sel_hi:[1,0]
	v_pk_add_f32 v[236:237], v[236:237], 1.0 op_sel_hi:[1,0]
	v_pk_add_f32 v[238:239], v[238:239], 1.0 op_sel_hi:[1,0]
	v_pk_add_f32 v[240:241], v[240:241], 1.0 op_sel_hi:[1,0]
	v_rcp_f32_e32 v234, v234
	v_rcp_f32_e32 v235, v235
	v_rcp_f32_e32 v236, v236
	v_rcp_f32_e32 v237, v237
	v_rcp_f32_e32 v238, v238
	v_rcp_f32_e32 v239, v239
	v_rcp_f32_e32 v240, v240
	v_rcp_f32_e32 v241, v241
	v_pk_mul_f32 v[226:227], v[226:227], v[234:235]
	v_pk_mul_f32 v[228:229], v[228:229], v[236:237]
	v_pk_mul_f32 v[230:231], v[230:231], v[238:239]
	v_pk_mul_f32 v[232:233], v[232:233], v[240:241]
	v_cvt_pk_bf16_f32 v250, v226, v227
	v_cvt_pk_bf16_f32 v251, v228, v229
	v_cvt_pk_bf16_f32 v252, v230, v231
	v_cvt_pk_bf16_f32 v253, v232, v233
	v_bitop3_b32 v93, v118, s55, v119 bitop3:0xde
	v_mul_f32_e32 v224, 0xbfb8aa3b, v153
	v_mul_f32_e32 v225, v153, v153
	v_pk_mul_f32 v[234:235], v[108:109], v[224:225] op_sel_hi:[1,0]
	v_pk_mul_f32 v[236:237], v[110:111], v[224:225] op_sel_hi:[1,0]
	v_pk_mul_f32 v[238:239], v[100:101], v[224:225] op_sel_hi:[1,0]
	v_pk_mul_f32 v[240:241], v[102:103], v[224:225] op_sel_hi:[1,0]
	v_pk_mul_f32 v[226:227], v[108:109], v[104:105]
	v_pk_mul_f32 v[228:229], v[110:111], v[106:107]
	v_pk_mul_f32 v[230:231], v[100:101], v[96:97]
	v_pk_mul_f32 v[232:233], v[102:103], v[98:99]
	v_exp_f32_e32 v234, v234
	v_exp_f32_e32 v235, v235
	v_exp_f32_e32 v236, v236
	v_exp_f32_e32 v237, v237
	v_exp_f32_e32 v238, v238
	v_exp_f32_e32 v239, v239
	v_exp_f32_e32 v240, v240
	v_exp_f32_e32 v241, v241
	v_pk_mul_f32 v[226:227], v[226:227], v[224:225] op_sel:[0,1] op_sel_hi:[1,1]
	v_pk_mul_f32 v[228:229], v[228:229], v[224:225] op_sel:[0,1] op_sel_hi:[1,1]
; __host__ __device__ __forceinline__ size_t tiled_off(int row, int col, int K) { return ((size_t)(row >> 7) * (K >> 6) + (col >> 6)) * 8192 + (lds_byte(row & 127, col & 63) >> 1); }
; __device__ __forceinline__ unsigned cvt_pk_bf16(float lo, float hi) { unsigned r; asm volatile("v_cvt_pk_bf16_f32 %0, %1, %2" : "=v"(r) : "v"(lo), "v"(hi)); return r; }
; __device__ __forceinline__ float fast_sigmoid(float x) { return __builtin_amdgcn_rcpf(1.0f + __builtin_amdgcn_exp2f(x * -1.4426950408889634f)); }
;     __device__ __forceinline__ void operator()(const f32x4 (&acc)[2][2][4][2], const Unit& u, int wr, int wc, int fr, int fq, const PG8_LAS float* rtab) const {
;     ...
;             for (int m = 0; m < 4; ++m) { const float r = rs[ai][m]; float o[8];
; #pragma unroll
;                 for (int n = 0; n < 2; ++n) { const f32x4 a = acc[ai][0][m][n] * r + bv[n], g = acc[ai][1][m][n] * r + bg[n];
; #pragma unroll
;                     for (int e = 0; e < 4; ++e) o[4 * n + e] = (MODE == 0) ? a[e] * fast_sigmoid(g[e]) : a[e] * fast_sigmoid(a[e]) * g[e]; }
;                 u32x4 w; w.x = cvt_pk_bf16(o[0], o[1]); w.y = cvt_pk_bf16(o[2], o[3]); w.z = cvt_pk_bf16(o[4], o[5]); w.w = cvt_pk_bf16(o[6], o[7]);
;                 if (MODE == 1) *(u32x4*)(O + tiled_off(row0 + ai * HALF + m * 16, lcol, ldc)) = w;
	v_pk_mul_f32 v[230:231], v[230:231], v[224:225] op_sel:[0,1] op_sel_hi:[1,1]
	v_pk_mul_f32 v[232:233], v[232:233], v[224:225] op_sel:[0,1] op_sel_hi:[1,1]
	v_pk_add_f32 v[234:235], v[234:235], 1.0 op_sel_hi:[1,0]
	v_pk_add_f32 v[236:237], v[236:237], 1.0 op_sel_hi:[1,0]
	v_pk_add_f32 v[238:239], v[238:239], 1.0 op_sel_hi:[1,0]
	v_pk_add_f32 v[240:241], v[240:241], 1.0 op_sel_hi:[1,0]
	v_rcp_f32_e32 v234, v234
	v_rcp_f32_e32 v235, v235
	v_rcp_f32_e32 v236, v236
	v_rcp_f32_e32 v237, v237
	v_rcp_f32_e32 v238, v238
	v_rcp_f32_e32 v239, v239
	v_rcp_f32_e32 v240, v240
	v_rcp_f32_e32 v241, v241
	v_pk_mul_f32 v[226:227], v[226:227], v[234:235]
	v_pk_mul_f32 v[228:229], v[228:229], v[236:237]
	v_pk_mul_f32 v[230:231], v[230:231], v[238:239]
	v_pk_mul_f32 v[232:233], v[232:233], v[240:241]
	v_cvt_pk_bf16_f32 v246, v226, v227
	v_cvt_pk_bf16_f32 v247, v228, v229
	v_cvt_pk_bf16_f32 v248, v230, v231
	v_cvt_pk_bf16_f32 v249, v232, v233
	global_store_dwordx4 v93, v[246:249], s[68:69]
	s_or_b32 s55, s53, 32
	s_lshr_b32 s55, s55, 3
	s_and_b32 s55, s55, 12
	s_or_b32 s55, s55, s41
	s_lshl_b32 s55, s55, 10
	v_bitop3_b32 v87, v118, s55, v119 bitop3:0xde
	global_store_dwordx4 v87, v[250:253], s[68:69]
	s_or_b32 s53, s53, 48
	s_lshr_b32 s53, s53, 3
	s_and_b32 s53, s53, 14
	s_or_b32 s53, s53, s41
	s_lshl_b32 s53, s53, 10
	v_mul_f32_e32 v224, 0xbfb8aa3b, v141
	v_mul_f32_e32 v225, v141, v141
	v_pk_mul_f32 v[234:235], v[76:77], v[224:225] op_sel_hi:[1,0]
	v_pk_mul_f32 v[236:237], v[78:79], v[224:225] op_sel_hi:[1,0]
	v_pk_mul_f32 v[238:239], v[68:69], v[224:225] op_sel_hi:[1,0]
	v_pk_mul_f32 v[240:241], v[70:71], v[224:225] op_sel_hi:[1,0]
	v_pk_mul_f32 v[226:227], v[76:77], v[72:73]
	v_pk_mul_f32 v[228:229], v[78:79], v[74:75]
	v_pk_mul_f32 v[230:231], v[68:69], v[64:65]
	v_pk_mul_f32 v[232:233], v[70:71], v[66:67]
	v_exp_f32_e32 v234, v234
	v_exp_f32_e32 v235, v235
	v_exp_f32_e32 v236, v236
	v_exp_f32_e32 v237, v237
	v_exp_f32_e32 v238, v238
	v_exp_f32_e32 v239, v239
	v_exp_f32_e32 v240, v240
	v_exp_f32_e32 v241, v241
	v_pk_mul_f32 v[226:227], v[226:227], v[224:225] op_sel:[0,1] op_sel_hi:[1,1]
	v_pk_mul_f32 v[228:229], v[228:229], v[224:225] op_sel:[0,1] op_sel_hi:[1,1]
	v_pk_mul_f32 v[230:231], v[230:231], v[224:225] op_sel:[0,1] op_sel_hi:[1,1]
	v_pk_mul_f32 v[232:233], v[232:233], v[224:225] op_sel:[0,1] op_sel_hi:[1,1]
	v_pk_add_f32 v[234:235], v[234:235], 1.0 op_sel_hi:[1,0]
	v_pk_add_f32 v[236:237], v[236:237], 1.0 op_sel_hi:[1,0]
	v_pk_add_f32 v[238:239], v[238:239], 1.0 op_sel_hi:[1,0]
	v_pk_add_f32 v[240:241], v[240:241], 1.0 op_sel_hi:[1,0]
	v_rcp_f32_e32 v234, v234
	v_rcp_f32_e32 v235, v235
	v_rcp_f32_e32 v236, v236
	v_rcp_f32_e32 v237, v237
	v_rcp_f32_e32 v238, v238
	v_rcp_f32_e32 v239, v239
	v_rcp_f32_e32 v240, v240
	v_rcp_f32_e32 v241, v241
	v_pk_mul_f32 v[226:227], v[226:227], v[234:235]
	v_pk_mul_f32 v[228:229], v[228:229], v[236:237]
	v_pk_mul_f32 v[230:231], v[230:231], v[238:239]
	v_pk_mul_f32 v[232:233], v[232:233], v[240:241]
	v_cvt_pk_bf16_f32 v242, v226, v227
	v_cvt_pk_bf16_f32 v243, v228, v229
	v_cvt_pk_bf16_f32 v244, v230, v231
	v_cvt_pk_bf16_f32 v245, v232, v233
	v_bitop3_b32 v68, v118, s53, v119 bitop3:0xde
	global_store_dwordx4 v68, v[242:245], s[68:69]
	s_andn2_b64 vcc, exec, s[4:5]
	s_mov_b64 s[4:5], -1
	v_add_u32_e32 v67, 0x80, v151
	v_ashrrev_i32_e32 v66, 7, v67
	v_mul_f32_e32 v224, 0xbfb8aa3b, v138
	v_mul_f32_e32 v225, v138, v138
	v_pk_mul_f32 v[234:235], v[60:61], v[224:225] op_sel_hi:[1,0]
	v_pk_mul_f32 v[236:237], v[62:63], v[224:225] op_sel_hi:[1,0]
	v_pk_mul_f32 v[238:239], v[52:53], v[224:225] op_sel_hi:[1,0]
	v_pk_mul_f32 v[240:241], v[54:55], v[224:225] op_sel_hi:[1,0]
	v_pk_mul_f32 v[226:227], v[60:61], v[56:57]
	v_pk_mul_f32 v[228:229], v[62:63], v[58:59]
	v_pk_mul_f32 v[230:231], v[52:53], v[48:49]
	v_pk_mul_f32 v[232:233], v[54:55], v[50:51]
	v_exp_f32_e32 v234, v234
	v_exp_f32_e32 v235, v235
	v_exp_f32_e32 v236, v236
	v_exp_f32_e32 v237, v237
	v_exp_f32_e32 v238, v238
	v_exp_f32_e32 v239, v239
	v_exp_f32_e32 v240, v240
	v_exp_f32_e32 v241, v241
	v_pk_mul_f32 v[226:227], v[226:227], v[224:225] op_sel:[0,1] op_sel_hi:[1,1]
	v_pk_mul_f32 v[228:229], v[228:229], v[224:225] op_sel:[0,1] op_sel_hi:[1,1]
	v_pk_mul_f32 v[230:231], v[230:231], v[224:225] op_sel:[0,1] op_sel_hi:[1,1]
	v_pk_mul_f32 v[232:233], v[232:233], v[224:225] op_sel:[0,1] op_sel_hi:[1,1]
	v_pk_add_f32 v[234:235], v[234:235], 1.0 op_sel_hi:[1,0]
	v_pk_add_f32 v[236:237], v[236:237], 1.0 op_sel_hi:[1,0]
	v_pk_add_f32 v[238:239], v[238:239], 1.0 op_sel_hi:[1,0]
	v_pk_add_f32 v[240:241], v[240:241], 1.0 op_sel_hi:[1,0]
	v_rcp_f32_e32 v234, v234
	v_rcp_f32_e32 v235, v235
	v_rcp_f32_e32 v236, v236
	v_rcp_f32_e32 v237, v237
	v_rcp_f32_e32 v238, v238
	v_rcp_f32_e32 v239, v239
	v_rcp_f32_e32 v240, v240
	v_rcp_f32_e32 v241, v241
	v_pk_mul_f32 v[226:227], v[226:227], v[234:235]
	v_pk_mul_f32 v[228:229], v[228:229], v[236:237]
	v_pk_mul_f32 v[230:231], v[230:231], v[238:239]
	v_pk_mul_f32 v[232:233], v[232:233], v[240:241]
	v_cvt_pk_bf16_f32 v246, v226, v227
	v_cvt_pk_bf16_f32 v247, v228, v229
	v_cvt_pk_bf16_f32 v248, v230, v231
	v_cvt_pk_bf16_f32 v249, v232, v233
	v_lshlrev_b32_e32 v55, 2, v67
	v_and_b32_e32 v55, 32, v55
	v_lshlrev_b32_e32 v54, 6, v67
	v_and_or_b32 v54, v54, s40, v143
	v_bitop3_b32 v130, v54, s42, v55 bitop3:0xde
	v_mul_lo_u32 v48, v66, 44
	v_ashrrev_i32_e32 v49, 31, v48
	v_lshl_add_u64 v[48:49], v[48:49], 0, s[60:61]
	v_lshlrev_b64 v[48:49], 14, v[48:49]
	v_lshl_add_u64 v[48:49], s[14:15], 0, v[48:49]
	v_lshl_add_u64 v[56:57], v[48:49], 0, v[130:131]
	global_store_dwordx4 v[56:57], v[246:249], off
	s_nop 0
	v_mul_f32_e32 v224, 0xbfb8aa3b, v139
; __host__ __device__ __forceinline__ size_t tiled_off(int row, int col, int K) { return ((size_t)(row >> 7) * (K >> 6) + (col >> 6)) * 8192 + (lds_byte(row & 127, col & 63) >> 1); }
; __device__ __forceinline__ unsigned cvt_pk_bf16(float lo, float hi) { unsigned r; asm volatile("v_cvt_pk_bf16_f32 %0, %1, %2" : "=v"(r) : "v"(lo), "v"(hi)); return r; }
; __device__ __forceinline__ float fast_sigmoid(float x) { return __builtin_amdgcn_rcpf(1.0f + __builtin_amdgcn_exp2f(x * -1.4426950408889634f)); }
;     __device__ __forceinline__ void operator()(const f32x4 (&acc)[2][2][4][2], const Unit& u, int wr, int wc, int fr, int fq, const PG8_LAS float* rtab) const {
;     ...
;             for (int m = 0; m < 4; ++m) { const float r = rs[ai][m]; float o[8];
; #pragma unroll
;                 for (int n = 0; n < 2; ++n) { const f32x4 a = acc[ai][0][m][n] * r + bv[n], g = acc[ai][1][m][n] * r + bg[n];
; #pragma unroll
;                     for (int e = 0; e < 4; ++e) o[4 * n + e] = (MODE == 0) ? a[e] * fast_sigmoid(g[e]) : a[e] * fast_sigmoid(a[e]) * g[e]; }
;                 u32x4 w; w.x = cvt_pk_bf16(o[0], o[1]); w.y = cvt_pk_bf16(o[2], o[3]); w.z = cvt_pk_bf16(o[4], o[5]); w.w = cvt_pk_bf16(o[6], o[7]);
;                 if (MODE == 1) *(u32x4*)(O + tiled_off(row0 + ai * HALF + m * 16, lcol, ldc)) = w;
;                 else *(u32x4*)(O + (size_t)(row0 + ai * HALF + m * 16) * ldc + lcol) = w; }
	v_mul_f32_e32 v225, v139, v139
	v_pk_mul_f32 v[234:235], v[44:45], v[224:225] op_sel_hi:[1,0]
	v_pk_mul_f32 v[236:237], v[46:47], v[224:225] op_sel_hi:[1,0]
	v_pk_mul_f32 v[238:239], v[36:37], v[224:225] op_sel_hi:[1,0]
	v_pk_mul_f32 v[240:241], v[38:39], v[224:225] op_sel_hi:[1,0]
	v_pk_mul_f32 v[226:227], v[44:45], v[40:41]
	v_pk_mul_f32 v[228:229], v[46:47], v[42:43]
	v_pk_mul_f32 v[230:231], v[36:37], v[32:33]
	v_pk_mul_f32 v[232:233], v[38:39], v[34:35]
	v_exp_f32_e32 v234, v234
	v_exp_f32_e32 v235, v235
	v_exp_f32_e32 v236, v236
	v_exp_f32_e32 v237, v237
	v_exp_f32_e32 v238, v238
	v_exp_f32_e32 v239, v239
	v_exp_f32_e32 v240, v240
	v_exp_f32_e32 v241, v241
	v_pk_mul_f32 v[226:227], v[226:227], v[224:225] op_sel:[0,1] op_sel_hi:[1,1]
	v_pk_mul_f32 v[228:229], v[228:229], v[224:225] op_sel:[0,1] op_sel_hi:[1,1]
	v_pk_mul_f32 v[230:231], v[230:231], v[224:225] op_sel:[0,1] op_sel_hi:[1,1]
	v_pk_mul_f32 v[232:233], v[232:233], v[224:225] op_sel:[0,1] op_sel_hi:[1,1]
	v_pk_add_f32 v[234:235], v[234:235], 1.0 op_sel_hi:[1,0]
	v_pk_add_f32 v[236:237], v[236:237], 1.0 op_sel_hi:[1,0]
	v_pk_add_f32 v[238:239], v[238:239], 1.0 op_sel_hi:[1,0]
	v_pk_add_f32 v[240:241], v[240:241], 1.0 op_sel_hi:[1,0]
	v_rcp_f32_e32 v234, v234
	v_rcp_f32_e32 v235, v235
	v_rcp_f32_e32 v236, v236
	v_rcp_f32_e32 v237, v237
	v_rcp_f32_e32 v238, v238
	v_rcp_f32_e32 v239, v239
	v_rcp_f32_e32 v240, v240
	v_rcp_f32_e32 v241, v241
	v_pk_mul_f32 v[226:227], v[226:227], v[234:235]
	v_pk_mul_f32 v[228:229], v[228:229], v[236:237]
	v_pk_mul_f32 v[230:231], v[230:231], v[238:239]
	v_pk_mul_f32 v[232:233], v[232:233], v[240:241]
	v_cvt_pk_bf16_f32 v250, v226, v227
	v_cvt_pk_bf16_f32 v251, v228, v229
	v_cvt_pk_bf16_f32 v252, v230, v231
	v_cvt_pk_bf16_f32 v253, v232, v233
	v_add_u32_e32 v36, 0x90, v151
	v_lshrrev_b32_e32 v37, 3, v36
	v_and_or_b32 v37, v37, 10, s41
	v_lshlrev_b32_e32 v38, 6, v36
	v_lshlrev_b32_e32 v36, 2, v36
	v_and_or_b32 v38, v38, s40, v143
	v_lshlrev_b32_e32 v37, 10, v37
	v_and_b32_e32 v36, 32, v36
	v_bitop3_b32 v130, v38, v37, v36 bitop3:0xde
	v_mul_f32_e32 v224, 0xbfb8aa3b, v136
	v_mul_f32_e32 v225, v136, v136
	v_pk_mul_f32 v[234:235], v[28:29], v[224:225] op_sel_hi:[1,0]
	v_pk_mul_f32 v[236:237], v[30:31], v[224:225] op_sel_hi:[1,0]
	v_pk_mul_f32 v[238:239], v[20:21], v[224:225] op_sel_hi:[1,0]
	v_pk_mul_f32 v[240:241], v[22:23], v[224:225] op_sel_hi:[1,0]
	v_pk_mul_f32 v[226:227], v[28:29], v[24:25]
	v_pk_mul_f32 v[228:229], v[30:31], v[26:27]
	v_pk_mul_f32 v[230:231], v[20:21], v[16:17]
	v_pk_mul_f32 v[232:233], v[22:23], v[18:19]
	v_exp_f32_e32 v234, v234
	v_exp_f32_e32 v235, v235
	v_exp_f32_e32 v236, v236
	v_exp_f32_e32 v237, v237
	v_exp_f32_e32 v238, v238
	v_exp_f32_e32 v239, v239
	v_exp_f32_e32 v240, v240
	v_exp_f32_e32 v241, v241
	v_pk_mul_f32 v[226:227], v[226:227], v[224:225] op_sel:[0,1] op_sel_hi:[1,1]
	v_pk_mul_f32 v[228:229], v[228:229], v[224:225] op_sel:[0,1] op_sel_hi:[1,1]
	v_pk_mul_f32 v[230:231], v[230:231], v[224:225] op_sel:[0,1] op_sel_hi:[1,1]
	v_pk_mul_f32 v[232:233], v[232:233], v[224:225] op_sel:[0,1] op_sel_hi:[1,1]
	v_pk_add_f32 v[234:235], v[234:235], 1.0 op_sel_hi:[1,0]
	v_pk_add_f32 v[236:237], v[236:237], 1.0 op_sel_hi:[1,0]
	v_pk_add_f32 v[238:239], v[238:239], 1.0 op_sel_hi:[1,0]
	v_pk_add_f32 v[240:241], v[240:241], 1.0 op_sel_hi:[1,0]
	v_rcp_f32_e32 v234, v234
	v_rcp_f32_e32 v235, v235
	v_rcp_f32_e32 v236, v236
	v_rcp_f32_e32 v237, v237
	v_rcp_f32_e32 v238, v238
	v_rcp_f32_e32 v239, v239
	v_rcp_f32_e32 v240, v240
	v_rcp_f32_e32 v241, v241
	v_pk_mul_f32 v[226:227], v[226:227], v[234:235]
	v_pk_mul_f32 v[228:229], v[228:229], v[236:237]
	v_pk_mul_f32 v[230:231], v[230:231], v[238:239]
	v_pk_mul_f32 v[232:233], v[232:233], v[240:241]
	v_cvt_pk_bf16_f32 v242, v226, v227
	v_cvt_pk_bf16_f32 v243, v228, v229
	v_cvt_pk_bf16_f32 v244, v230, v231
	v_cvt_pk_bf16_f32 v245, v232, v233
	v_lshl_add_u64 v[28:29], v[48:49], 0, v[130:131]
	global_store_dwordx4 v[28:29], v[250:253], off
	v_add_u32_e32 v20, 0xa0, v151
	v_lshrrev_b32_e32 v21, 3, v20
	v_and_or_b32 v21, v21, 12, s41
	v_lshlrev_b32_e32 v22, 6, v20
	v_lshlrev_b32_e32 v20, 2, v20
	v_and_or_b32 v22, v22, s40, v143
	v_lshlrev_b32_e32 v21, 10, v21
	v_and_b32_e32 v20, 32, v20
	v_bitop3_b32 v130, v22, v21, v20 bitop3:0xde
	v_lshl_add_u64 v[22:23], v[48:49], 0, v[130:131]
	global_store_dwordx4 v[22:23], v[242:245], off
	v_mul_f32_e32 v224, 0xbfb8aa3b, v137
	v_mul_f32_e32 v225, v137, v137
	v_pk_mul_f32 v[234:235], v[12:13], v[224:225] op_sel_hi:[1,0]
	v_pk_mul_f32 v[236:237], v[14:15], v[224:225] op_sel_hi:[1,0]
	v_pk_mul_f32 v[238:239], v[4:5], v[224:225] op_sel_hi:[1,0]
	v_pk_mul_f32 v[240:241], v[6:7], v[224:225] op_sel_hi:[1,0]
	v_pk_mul_f32 v[226:227], v[12:13], v[8:9]
	v_pk_mul_f32 v[228:229], v[14:15], v[10:11]
	v_pk_mul_f32 v[230:231], v[4:5], v[0:1]
	v_pk_mul_f32 v[232:233], v[6:7], v[2:3]
	v_exp_f32_e32 v234, v234
	v_exp_f32_e32 v235, v235
	v_exp_f32_e32 v236, v236
	v_exp_f32_e32 v237, v237
	v_exp_f32_e32 v238, v238
	v_exp_f32_e32 v239, v239
	v_exp_f32_e32 v240, v240
	v_exp_f32_e32 v241, v241
	v_pk_mul_f32 v[226:227], v[226:227], v[224:225] op_sel:[0,1] op_sel_hi:[1,1]
	v_pk_mul_f32 v[228:229], v[228:229], v[224:225] op_sel:[0,1] op_sel_hi:[1,1]
	v_pk_mul_f32 v[230:231], v[230:231], v[224:225] op_sel:[0,1] op_sel_hi:[1,1]
	v_pk_mul_f32 v[232:233], v[232:233], v[224:225] op_sel:[0,1] op_sel_hi:[1,1]
	v_pk_add_f32 v[234:235], v[234:235], 1.0 op_sel_hi:[1,0]
	v_pk_add_f32 v[236:237], v[236:237], 1.0 op_sel_hi:[1,0]
	v_pk_add_f32 v[238:239], v[238:239], 1.0 op_sel_hi:[1,0]
	v_pk_add_f32 v[240:241], v[240:241], 1.0 op_sel_hi:[1,0]
	v_rcp_f32_e32 v234, v234
	v_rcp_f32_e32 v235, v235
	v_rcp_f32_e32 v236, v236
	v_rcp_f32_e32 v237, v237
	v_rcp_f32_e32 v238, v238
	v_rcp_f32_e32 v239, v239
	v_rcp_f32_e32 v240, v240
	v_rcp_f32_e32 v241, v241
	v_pk_mul_f32 v[226:227], v[226:227], v[234:235]
	v_pk_mul_f32 v[228:229], v[228:229], v[236:237]
	v_pk_mul_f32 v[230:231], v[230:231], v[238:239]
	v_pk_mul_f32 v[232:233], v[232:233], v[240:241]
	v_cvt_pk_bf16_f32 v246, v226, v227
	v_cvt_pk_bf16_f32 v247, v228, v229
	v_cvt_pk_bf16_f32 v248, v230, v231
	v_cvt_pk_bf16_f32 v249, v232, v233
	v_add_u32_e32 v4, 0xb0, v151
	v_lshrrev_b32_e32 v5, 3, v4
	v_and_or_b32 v5, v5, 14, s41
	v_lshlrev_b32_e32 v6, 6, v4
	v_lshlrev_b32_e32 v4, 2, v4
	v_and_or_b32 v6, v6, s40, v143
	v_lshlrev_b32_e32 v5, 10, v5
	v_and_b32_e32 v4, 32, v4
	v_bitop3_b32 v130, v6, v5, v4 bitop3:0xde
	v_lshl_add_u64 v[4:5], v[48:49], 0, v[130:131]
	global_store_dwordx4 v[4:5], v[246:249], off
	s_cbranch_vccnz .LBB0_786
	s_and_saveexec_b64 s[4:5], s[2:3]
	s_cbranch_execz .LBB0_796
	v_lshl_or_b32 v0, s54, 8, v208
	v_ashrrev_i32_e32 v1, 31, v0
	v_lshlrev_b64 v[0:1], 6, v[0:1]
	v_lshl_add_u64 v[12:13], s[24:25], 0, v[0:1]
	global_load_dwordx4 v[0:3], v[12:13], off
	global_load_dwordx4 v[4:7], v[12:13], off offset:16
	global_load_dwordx4 v[8:11], v[12:13], off offset:32
	s_nop 0
	global_load_dwordx4 v[12:15], v[12:13], off offset:48
	s_lshl_b32 s53, s78, 10
	s_and_b32 s53, s53, 0x400
	s_waitcnt vmcnt(0)
	v_pk_add_f32 v[2:3], v[2:3], v[6:7]
	v_pk_add_f32 v[0:1], v[0:1], v[4:5]
	v_pk_add_f32 v[4:5], v[10:11], v[14:15]
	v_pk_add_f32 v[6:7], v[8:9], v[12:13]
	v_pk_add_f32 v[2:3], v[2:3], v[4:5]
	v_pk_add_f32 v[0:1], v[0:1], v[6:7]
	s_nop 0
	v_pk_mov_b32 v[4:5], v[0:1], v[2:3] op_sel:[1,0]
	v_mov_b32_e32 v1, v3
	v_pk_add_f32 v[0:1], v[4:5], v[0:1]
	s_nop 0
	v_add_f32_e32 v0, v0, v1
	v_fmamk_f32 v0, v0, 0x3a800000, v150
	v_rsq_f32_e32 v0, v0
	v_add_u32_e32 v1, s53, v145
	ds_write_b32 v1, v0

; __host__ __device__ __forceinline__ size_t tiled_off(int row, int col, int K) { return ((size_t)(row >> 7) * (K >> 6) + (col >> 6)) * 8192 + (lds_byte(row & 127, col & 63) >> 1); }
; __device__ __forceinline__ unsigned cvt_pk_bf16(float lo, float hi) { unsigned r; asm volatile("v_cvt_pk_bf16_f32 %0, %1, %2" : "=v"(r) : "v"(lo), "v"(hi)); return r; }
; __device__ __forceinline__ float fast_sigmoid(float x) { return __builtin_amdgcn_rcpf(1.0f + __builtin_amdgcn_exp2f(x * -1.4426950408889634f)); }
;     __device__ __forceinline__ void operator()(const f32x4 (&acc)[2][2][4][2], const Unit& u, int wr, int wc, int fr, int fq, const PG8_LAS float* rtab) const {
;     ...
;             for (int m = 0; m < 4; ++m) { const float r = rs[ai][m]; float o[8];
; #pragma unroll
;                 for (int n = 0; n < 2; ++n) { const f32x4 a = acc[ai][0][m][n] * r + bv[n], g = acc[ai][1][m][n] * r + bg[n];
; #pragma unroll
;                     for (int e = 0; e < 4; ++e) o[4 * n + e] = (MODE == 0) ? a[e] * fast_sigmoid(g[e]) : a[e] * fast_sigmoid(a[e]) * g[e]; }
;                 u32x4 w; w.x = cvt_pk_bf16(o[0], o[1]); w.y = cvt_pk_bf16(o[2], o[3]); w.z = cvt_pk_bf16(o[4], o[5]); w.w = cvt_pk_bf16(o[6], o[7]);
;                 if (MODE == 1) *(u32x4*)(O + tiled_off(row0 + ai * HALF + m * 16, lcol, ldc)) = w;
.LBB0_1628:
	s_lshl_b32 s45, s53, 10
	s_and_b32 s47, s45, 0x400
	v_add_u32_e32 v130, s47, v146
	ds_read2_b32 v[152:153], v130 offset1:16
	ds_read2_b32 v[140:141], v130 offset0:32 offset1:48
	ds_read2_b32 v[138:139], v130 offset0:128 offset1:144
	ds_read2_b32 v[136:137], v130 offset0:160 offset1:176
	s_waitcnt lgkmcnt(0)
	s_lshl_b32 s45, s52, 8
	s_add_i32 s45, s45, s62
	v_or_b32_e32 v151, s45, v142
	v_mul_f32_e32 v224, 0xbfb8aa3b, v152
	v_mul_f32_e32 v225, v152, v152
	v_pk_mul_f32 v[234:235], v[124:125], v[224:225] op_sel_hi:[1,0]
	v_pk_mul_f32 v[236:237], v[126:127], v[224:225] op_sel_hi:[1,0]
	v_pk_mul_f32 v[238:239], v[116:117], v[224:225] op_sel_hi:[1,0]
	v_pk_mul_f32 v[240:241], v[118:119], v[224:225] op_sel_hi:[1,0]
	v_pk_mul_f32 v[226:227], v[124:125], v[120:121]
	v_pk_mul_f32 v[228:229], v[126:127], v[122:123]
	v_pk_mul_f32 v[230:231], v[116:117], v[112:113]
	v_pk_mul_f32 v[232:233], v[118:119], v[114:115]
	v_exp_f32_e32 v234, v234
	v_exp_f32_e32 v235, v235
	v_exp_f32_e32 v236, v236
	v_exp_f32_e32 v237, v237
	v_exp_f32_e32 v238, v238
	v_exp_f32_e32 v239, v239
	v_exp_f32_e32 v240, v240
	v_exp_f32_e32 v241, v241
	v_pk_mul_f32 v[226:227], v[226:227], v[224:225] op_sel:[0,1] op_sel_hi:[1,1]
	v_pk_mul_f32 v[228:229], v[228:229], v[224:225] op_sel:[0,1] op_sel_hi:[1,1]
	v_pk_mul_f32 v[230:231], v[230:231], v[224:225] op_sel:[0,1] op_sel_hi:[1,1]
	v_pk_mul_f32 v[232:233], v[232:233], v[224:225] op_sel:[0,1] op_sel_hi:[1,1]
	v_pk_add_f32 v[234:235], v[234:235], 1.0 op_sel_hi:[1,0]
	v_pk_add_f32 v[236:237], v[236:237], 1.0 op_sel_hi:[1,0]
	v_pk_add_f32 v[238:239], v[238:239], 1.0 op_sel_hi:[1,0]
	v_pk_add_f32 v[240:241], v[240:241], 1.0 op_sel_hi:[1,0]
	v_rcp_f32_e32 v234, v234
	v_rcp_f32_e32 v235, v235
	v_rcp_f32_e32 v236, v236
	v_rcp_f32_e32 v237, v237
	v_rcp_f32_e32 v238, v238
	v_rcp_f32_e32 v239, v239
	v_rcp_f32_e32 v240, v240
	v_rcp_f32_e32 v241, v241
	v_pk_mul_f32 v[226:227], v[226:227], v[234:235]
	v_pk_mul_f32 v[228:229], v[228:229], v[236:237]
	v_pk_mul_f32 v[230:231], v[230:231], v[238:239]
	v_pk_mul_f32 v[232:233], v[232:233], v[240:241]
	v_cvt_pk_bf16_f32 v242, v226, v227
	v_cvt_pk_bf16_f32 v243, v228, v229
	v_cvt_pk_bf16_f32 v244, v230, v231
	v_cvt_pk_bf16_f32 v245, v232, v233
	v_lshlrev_b32_e32 v116, 6, v151
	v_and_or_b32 v118, v116, s64, v143
	v_lshlrev_b32_e32 v116, 2, v151
	v_and_b32_e32 v119, 32, v116
	s_lshl_b32 s47, s54, 7
	s_or_b32 s47, s47, s63
	s_ashr_i32 s52, s47, 6
	s_ashr_i32 s47, s45, 7
	s_mul_i32 s47, s47, 44
	s_ashr_i32 s53, s52, 31
	s_ashr_i32 s55, s47, 31
	s_add_u32 s54, s47, s52
	s_addc_u32 s55, s55, s53
	s_lshl_b64 s[54:55], s[54:55], 14
	s_add_u32 s54, s24, s54
	v_bitop3_b32 v120, v118, s66, v119 bitop3:0xde
	s_addc_u32 s55, s25, s55
	global_store_dwordx4 v120, v[242:245], s[54:55]
	s_or_b32 s47, s45, 16
	s_lshr_b32 s47, s47, 3
	s_and_b32 s47, s47, 10
	s_or_b32 s47, s47, s65
	s_lshl_b32 s47, s47, 10
	v_mul_f32_e32 v224, 0xbfb8aa3b, v140
	v_mul_f32_e32 v225, v140, v140
	v_pk_mul_f32 v[234:235], v[92:93], v[224:225] op_sel_hi:[1,0]
	v_pk_mul_f32 v[236:237], v[94:95], v[224:225] op_sel_hi:[1,0]
	v_pk_mul_f32 v[238:239], v[84:85], v[224:225] op_sel_hi:[1,0]
	v_pk_mul_f32 v[240:241], v[86:87], v[224:225] op_sel_hi:[1,0]
	v_pk_mul_f32 v[226:227], v[92:93], v[88:89]
	v_pk_mul_f32 v[228:229], v[94:95], v[90:91]
	v_pk_mul_f32 v[230:231], v[84:85], v[80:81]
	v_pk_mul_f32 v[232:233], v[86:87], v[82:83]
	v_exp_f32_e32 v234, v234
	v_exp_f32_e32 v235, v235
	v_exp_f32_e32 v236, v236
	v_exp_f32_e32 v237, v237
	v_exp_f32_e32 v238, v238
	v_exp_f32_e32 v239, v239
	v_exp_f32_e32 v240, v240
	v_exp_f32_e32 v241, v241
	v_pk_mul_f32 v[226:227], v[226:227], v[224:225] op_sel:[0,1] op_sel_hi:[1,1]
	v_pk_mul_f32 v[228:229], v[228:229], v[224:225] op_sel:[0,1] op_sel_hi:[1,1]
	v_pk_mul_f32 v[230:231], v[230:231], v[224:225] op_sel:[0,1] op_sel_hi:[1,1]
	v_pk_mul_f32 v[232:233], v[232:233], v[224:225] op_sel:[0,1] op_sel_hi:[1,1]
	v_pk_add_f32 v[234:235], v[234:235], 1.0 op_sel_hi:[1,0]
	v_pk_add_f32 v[236:237], v[236:237], 1.0 op_sel_hi:[1,0]
	v_pk_add_f32 v[238:239], v[238:239], 1.0 op_sel_hi:[1,0]
	v_pk_add_f32 v[240:241], v[240:241], 1.0 op_sel_hi:[1,0]
	v_rcp_f32_e32 v234, v234
	v_rcp_f32_e32 v235, v235
	v_rcp_f32_e32 v236, v236
	v_rcp_f32_e32 v237, v237
	v_rcp_f32_e32 v238, v238
	v_rcp_f32_e32 v239, v239
	v_rcp_f32_e32 v240, v240
	v_rcp_f32_e32 v241, v241
	v_pk_mul_f32 v[226:227], v[226:227], v[234:235]
	v_pk_mul_f32 v[228:229], v[228:229], v[236:237]
	v_pk_mul_f32 v[230:231], v[230:231], v[238:239]
	v_pk_mul_f32 v[232:233], v[232:233], v[240:241]
	v_cvt_pk_bf16_f32 v250, v226, v227
	v_cvt_pk_bf16_f32 v251, v228, v229
	v_cvt_pk_bf16_f32 v252, v230, v231
	v_cvt_pk_bf16_f32 v253, v232, v233
	v_bitop3_b32 v93, v118, s47, v119 bitop3:0xde
	v_mul_f32_e32 v224, 0xbfb8aa3b, v153
	v_mul_f32_e32 v225, v153, v153
	v_pk_mul_f32 v[234:235], v[108:109], v[224:225] op_sel_hi:[1,0]
	v_pk_mul_f32 v[236:237], v[110:111], v[224:225] op_sel_hi:[1,0]
	v_pk_mul_f32 v[238:239], v[100:101], v[224:225] op_sel_hi:[1,0]
	v_pk_mul_f32 v[240:241], v[102:103], v[224:225] op_sel_hi:[1,0]
	v_pk_mul_f32 v[226:227], v[108:109], v[104:105]
	v_pk_mul_f32 v[228:229], v[110:111], v[106:107]
	v_pk_mul_f32 v[230:231], v[100:101], v[96:97]
	v_pk_mul_f32 v[232:233], v[102:103], v[98:99]
	v_exp_f32_e32 v234, v234
	v_exp_f32_e32 v235, v235
	v_exp_f32_e32 v236, v236
	v_exp_f32_e32 v237, v237
	v_exp_f32_e32 v238, v238
	v_exp_f32_e32 v239, v239
	v_exp_f32_e32 v240, v240
	v_exp_f32_e32 v241, v241
	v_pk_mul_f32 v[226:227], v[226:227], v[224:225] op_sel:[0,1] op_sel_hi:[1,1]
	v_pk_mul_f32 v[228:229], v[228:229], v[224:225] op_sel:[0,1] op_sel_hi:[1,1]
; __host__ __device__ __forceinline__ size_t tiled_off(int row, int col, int K) { return ((size_t)(row >> 7) * (K >> 6) + (col >> 6)) * 8192 + (lds_byte(row & 127, col & 63) >> 1); }
; __device__ __forceinline__ unsigned cvt_pk_bf16(float lo, float hi) { unsigned r; asm volatile("v_cvt_pk_bf16_f32 %0, %1, %2" : "=v"(r) : "v"(lo), "v"(hi)); return r; }
; __device__ __forceinline__ float fast_sigmoid(float x) { return __builtin_amdgcn_rcpf(1.0f + __builtin_amdgcn_exp2f(x * -1.4426950408889634f)); }
;     __device__ __forceinline__ void operator()(const f32x4 (&acc)[2][2][4][2], const Unit& u, int wr, int wc, int fr, int fq, const PG8_LAS float* rtab) const {
;     ...
;             for (int m = 0; m < 4; ++m) { const float r = rs[ai][m]; float o[8];
; #pragma unroll
;                 for (int n = 0; n < 2; ++n) { const f32x4 a = acc[ai][0][m][n] * r + bv[n], g = acc[ai][1][m][n] * r + bg[n];
; #pragma unroll
;                     for (int e = 0; e < 4; ++e) o[4 * n + e] = (MODE == 0) ? a[e] * fast_sigmoid(g[e]) : a[e] * fast_sigmoid(a[e]) * g[e]; }
;                 u32x4 w; w.x = cvt_pk_bf16(o[0], o[1]); w.y = cvt_pk_bf16(o[2], o[3]); w.z = cvt_pk_bf16(o[4], o[5]); w.w = cvt_pk_bf16(o[6], o[7]);
;                 if (MODE == 1) *(u32x4*)(O + tiled_off(row0 + ai * HALF + m * 16, lcol, ldc)) = w;
	v_pk_mul_f32 v[230:231], v[230:231], v[224:225] op_sel:[0,1] op_sel_hi:[1,1]
	v_pk_mul_f32 v[232:233], v[232:233], v[224:225] op_sel:[0,1] op_sel_hi:[1,1]
	v_pk_add_f32 v[234:235], v[234:235], 1.0 op_sel_hi:[1,0]
	v_pk_add_f32 v[236:237], v[236:237], 1.0 op_sel_hi:[1,0]
	v_pk_add_f32 v[238:239], v[238:239], 1.0 op_sel_hi:[1,0]
	v_pk_add_f32 v[240:241], v[240:241], 1.0 op_sel_hi:[1,0]
	v_rcp_f32_e32 v234, v234
	v_rcp_f32_e32 v235, v235
	v_rcp_f32_e32 v236, v236
	v_rcp_f32_e32 v237, v237
	v_rcp_f32_e32 v238, v238
	v_rcp_f32_e32 v239, v239
	v_rcp_f32_e32 v240, v240
	v_rcp_f32_e32 v241, v241
	v_pk_mul_f32 v[226:227], v[226:227], v[234:235]
	v_pk_mul_f32 v[228:229], v[228:229], v[236:237]
	v_pk_mul_f32 v[230:231], v[230:231], v[238:239]
	v_pk_mul_f32 v[232:233], v[232:233], v[240:241]
	v_cvt_pk_bf16_f32 v246, v226, v227
	v_cvt_pk_bf16_f32 v247, v228, v229
	v_cvt_pk_bf16_f32 v248, v230, v231
	v_cvt_pk_bf16_f32 v249, v232, v233
	global_store_dwordx4 v93, v[246:249], s[54:55]
	s_or_b32 s47, s45, 32
	s_lshr_b32 s47, s47, 3
	s_and_b32 s47, s47, 12
	s_or_b32 s47, s47, s65
	s_lshl_b32 s47, s47, 10
	v_bitop3_b32 v87, v118, s47, v119 bitop3:0xde
	global_store_dwordx4 v87, v[250:253], s[54:55]
	s_or_b32 s45, s45, 48
	s_lshr_b32 s45, s45, 3
	s_and_b32 s45, s45, 14
	s_or_b32 s45, s45, s65
	s_lshl_b32 s45, s45, 10
	v_mul_f32_e32 v224, 0xbfb8aa3b, v141
	v_mul_f32_e32 v225, v141, v141
	v_pk_mul_f32 v[234:235], v[76:77], v[224:225] op_sel_hi:[1,0]
	v_pk_mul_f32 v[236:237], v[78:79], v[224:225] op_sel_hi:[1,0]
	v_pk_mul_f32 v[238:239], v[68:69], v[224:225] op_sel_hi:[1,0]
	v_pk_mul_f32 v[240:241], v[70:71], v[224:225] op_sel_hi:[1,0]
	v_pk_mul_f32 v[226:227], v[76:77], v[72:73]
	v_pk_mul_f32 v[228:229], v[78:79], v[74:75]
	v_pk_mul_f32 v[230:231], v[68:69], v[64:65]
	v_pk_mul_f32 v[232:233], v[70:71], v[66:67]
	v_exp_f32_e32 v234, v234
	v_exp_f32_e32 v235, v235
	v_exp_f32_e32 v236, v236
	v_exp_f32_e32 v237, v237
	v_exp_f32_e32 v238, v238
	v_exp_f32_e32 v239, v239
	v_exp_f32_e32 v240, v240
	v_exp_f32_e32 v241, v241
	v_pk_mul_f32 v[226:227], v[226:227], v[224:225] op_sel:[0,1] op_sel_hi:[1,1]
	v_pk_mul_f32 v[228:229], v[228:229], v[224:225] op_sel:[0,1] op_sel_hi:[1,1]
	v_pk_mul_f32 v[230:231], v[230:231], v[224:225] op_sel:[0,1] op_sel_hi:[1,1]
	v_pk_mul_f32 v[232:233], v[232:233], v[224:225] op_sel:[0,1] op_sel_hi:[1,1]
	v_pk_add_f32 v[234:235], v[234:235], 1.0 op_sel_hi:[1,0]
	v_pk_add_f32 v[236:237], v[236:237], 1.0 op_sel_hi:[1,0]
	v_pk_add_f32 v[238:239], v[238:239], 1.0 op_sel_hi:[1,0]
	v_pk_add_f32 v[240:241], v[240:241], 1.0 op_sel_hi:[1,0]
	v_rcp_f32_e32 v234, v234
	v_rcp_f32_e32 v235, v235
	v_rcp_f32_e32 v236, v236
	v_rcp_f32_e32 v237, v237
	v_rcp_f32_e32 v238, v238
	v_rcp_f32_e32 v239, v239
	v_rcp_f32_e32 v240, v240
	v_rcp_f32_e32 v241, v241
	v_pk_mul_f32 v[226:227], v[226:227], v[234:235]
	v_pk_mul_f32 v[228:229], v[228:229], v[236:237]
	v_pk_mul_f32 v[230:231], v[230:231], v[238:239]
	v_pk_mul_f32 v[232:233], v[232:233], v[240:241]
	v_cvt_pk_bf16_f32 v242, v226, v227
	v_cvt_pk_bf16_f32 v243, v228, v229
	v_cvt_pk_bf16_f32 v244, v230, v231
	v_cvt_pk_bf16_f32 v245, v232, v233
	v_bitop3_b32 v68, v118, s45, v119 bitop3:0xde
	global_store_dwordx4 v68, v[242:245], s[54:55]
	s_andn2_b64 vcc, exec, s[4:5]
	s_mov_b64 s[4:5], -1
	v_add_u32_e32 v67, 0x80, v151
	v_ashrrev_i32_e32 v66, 7, v67
	v_mul_f32_e32 v224, 0xbfb8aa3b, v138
	v_mul_f32_e32 v225, v138, v138
	v_pk_mul_f32 v[234:235], v[60:61], v[224:225] op_sel_hi:[1,0]
	v_pk_mul_f32 v[236:237], v[62:63], v[224:225] op_sel_hi:[1,0]
	v_pk_mul_f32 v[238:239], v[52:53], v[224:225] op_sel_hi:[1,0]
	v_pk_mul_f32 v[240:241], v[54:55], v[224:225] op_sel_hi:[1,0]
	v_pk_mul_f32 v[226:227], v[60:61], v[56:57]
	v_pk_mul_f32 v[228:229], v[62:63], v[58:59]
	v_pk_mul_f32 v[230:231], v[52:53], v[48:49]
	v_pk_mul_f32 v[232:233], v[54:55], v[50:51]
	v_exp_f32_e32 v234, v234
	v_exp_f32_e32 v235, v235
	v_exp_f32_e32 v236, v236
	v_exp_f32_e32 v237, v237
	v_exp_f32_e32 v238, v238
	v_exp_f32_e32 v239, v239
	v_exp_f32_e32 v240, v240
	v_exp_f32_e32 v241, v241
	v_pk_mul_f32 v[226:227], v[226:227], v[224:225] op_sel:[0,1] op_sel_hi:[1,1]
	v_pk_mul_f32 v[228:229], v[228:229], v[224:225] op_sel:[0,1] op_sel_hi:[1,1]
	v_pk_mul_f32 v[230:231], v[230:231], v[224:225] op_sel:[0,1] op_sel_hi:[1,1]
	v_pk_mul_f32 v[232:233], v[232:233], v[224:225] op_sel:[0,1] op_sel_hi:[1,1]
	v_pk_add_f32 v[234:235], v[234:235], 1.0 op_sel_hi:[1,0]
	v_pk_add_f32 v[236:237], v[236:237], 1.0 op_sel_hi:[1,0]
	v_pk_add_f32 v[238:239], v[238:239], 1.0 op_sel_hi:[1,0]
	v_pk_add_f32 v[240:241], v[240:241], 1.0 op_sel_hi:[1,0]
	v_rcp_f32_e32 v234, v234
	v_rcp_f32_e32 v235, v235
	v_rcp_f32_e32 v236, v236
	v_rcp_f32_e32 v237, v237
	v_rcp_f32_e32 v238, v238
	v_rcp_f32_e32 v239, v239
	v_rcp_f32_e32 v240, v240
	v_rcp_f32_e32 v241, v241
	v_pk_mul_f32 v[226:227], v[226:227], v[234:235]
	v_pk_mul_f32 v[228:229], v[228:229], v[236:237]
	v_pk_mul_f32 v[230:231], v[230:231], v[238:239]
	v_pk_mul_f32 v[232:233], v[232:233], v[240:241]
	v_cvt_pk_bf16_f32 v246, v226, v227
	v_cvt_pk_bf16_f32 v247, v228, v229
	v_cvt_pk_bf16_f32 v248, v230, v231
	v_cvt_pk_bf16_f32 v249, v232, v233
	v_lshlrev_b32_e32 v55, 2, v67
	v_and_b32_e32 v55, 32, v55
	v_lshlrev_b32_e32 v54, 6, v67
	v_and_or_b32 v54, v54, s64, v143
	v_bitop3_b32 v130, v54, s66, v55 bitop3:0xde
	v_mul_lo_u32 v48, v66, 44
	v_ashrrev_i32_e32 v49, 31, v48
	v_lshl_add_u64 v[48:49], v[48:49], 0, s[52:53]
	v_lshlrev_b64 v[48:49], 14, v[48:49]
	v_lshl_add_u64 v[48:49], s[24:25], 0, v[48:49]
	v_lshl_add_u64 v[56:57], v[48:49], 0, v[130:131]
	global_store_dwordx4 v[56:57], v[246:249], off
	s_nop 0
	v_mul_f32_e32 v224, 0xbfb8aa3b, v139
; __host__ __device__ __forceinline__ size_t tiled_off(int row, int col, int K) { return ((size_t)(row >> 7) * (K >> 6) + (col >> 6)) * 8192 + (lds_byte(row & 127, col & 63) >> 1); }
; __device__ __forceinline__ unsigned cvt_pk_bf16(float lo, float hi) { unsigned r; asm volatile("v_cvt_pk_bf16_f32 %0, %1, %2" : "=v"(r) : "v"(lo), "v"(hi)); return r; }
; __device__ __forceinline__ float fast_sigmoid(float x) { return __builtin_amdgcn_rcpf(1.0f + __builtin_amdgcn_exp2f(x * -1.4426950408889634f)); }
;     __device__ __forceinline__ void operator()(const f32x4 (&acc)[2][2][4][2], const Unit& u, int wr, int wc, int fr, int fq, const PG8_LAS float* rtab) const {
;     ...
;             for (int m = 0; m < 4; ++m) { const float r = rs[ai][m]; float o[8];
; #pragma unroll
;                 for (int n = 0; n < 2; ++n) { const f32x4 a = acc[ai][0][m][n] * r + bv[n], g = acc[ai][1][m][n] * r + bg[n];
; #pragma unroll
;                     for (int e = 0; e < 4; ++e) o[4 * n + e] = (MODE == 0) ? a[e] * fast_sigmoid(g[e]) : a[e] * fast_sigmoid(a[e]) * g[e]; }
;                 u32x4 w; w.x = cvt_pk_bf16(o[0], o[1]); w.y = cvt_pk_bf16(o[2], o[3]); w.z = cvt_pk_bf16(o[4], o[5]); w.w = cvt_pk_bf16(o[6], o[7]);
;                 if (MODE == 1) *(u32x4*)(O + tiled_off(row0 + ai * HALF + m * 16, lcol, ldc)) = w;
	v_mul_f32_e32 v225, v139, v139
	v_pk_mul_f32 v[234:235], v[44:45], v[224:225] op_sel_hi:[1,0]
	v_pk_mul_f32 v[236:237], v[46:47], v[224:225] op_sel_hi:[1,0]
	v_pk_mul_f32 v[238:239], v[36:37], v[224:225] op_sel_hi:[1,0]
	v_pk_mul_f32 v[240:241], v[38:39], v[224:225] op_sel_hi:[1,0]
	v_pk_mul_f32 v[226:227], v[44:45], v[40:41]
	v_pk_mul_f32 v[228:229], v[46:47], v[42:43]
	v_pk_mul_f32 v[230:231], v[36:37], v[32:33]
	v_pk_mul_f32 v[232:233], v[38:39], v[34:35]
	v_exp_f32_e32 v234, v234
	v_exp_f32_e32 v235, v235
	v_exp_f32_e32 v236, v236
	v_exp_f32_e32 v237, v237
	v_exp_f32_e32 v238, v238
	v_exp_f32_e32 v239, v239
	v_exp_f32_e32 v240, v240
	v_exp_f32_e32 v241, v241
	v_pk_mul_f32 v[226:227], v[226:227], v[224:225] op_sel:[0,1] op_sel_hi:[1,1]
	v_pk_mul_f32 v[228:229], v[228:229], v[224:225] op_sel:[0,1] op_sel_hi:[1,1]
	v_pk_mul_f32 v[230:231], v[230:231], v[224:225] op_sel:[0,1] op_sel_hi:[1,1]
	v_pk_mul_f32 v[232:233], v[232:233], v[224:225] op_sel:[0,1] op_sel_hi:[1,1]
	v_pk_add_f32 v[234:235], v[234:235], 1.0 op_sel_hi:[1,0]
	v_pk_add_f32 v[236:237], v[236:237], 1.0 op_sel_hi:[1,0]
	v_pk_add_f32 v[238:239], v[238:239], 1.0 op_sel_hi:[1,0]
	v_pk_add_f32 v[240:241], v[240:241], 1.0 op_sel_hi:[1,0]
	v_rcp_f32_e32 v234, v234
	v_rcp_f32_e32 v235, v235
	v_rcp_f32_e32 v236, v236
	v_rcp_f32_e32 v237, v237
	v_rcp_f32_e32 v238, v238
	v_rcp_f32_e32 v239, v239
	v_rcp_f32_e32 v240, v240
	v_rcp_f32_e32 v241, v241
	v_pk_mul_f32 v[226:227], v[226:227], v[234:235]
	v_pk_mul_f32 v[228:229], v[228:229], v[236:237]
	v_pk_mul_f32 v[230:231], v[230:231], v[238:239]
	v_pk_mul_f32 v[232:233], v[232:233], v[240:241]
	v_cvt_pk_bf16_f32 v250, v226, v227
	v_cvt_pk_bf16_f32 v251, v228, v229
	v_cvt_pk_bf16_f32 v252, v230, v231
	v_cvt_pk_bf16_f32 v253, v232, v233
	v_add_u32_e32 v36, 0x90, v151
	v_lshrrev_b32_e32 v37, 3, v36
	v_and_or_b32 v37, v37, 10, s65
	v_lshlrev_b32_e32 v38, 6, v36
	v_lshlrev_b32_e32 v36, 2, v36
	v_and_or_b32 v38, v38, s64, v143
	v_lshlrev_b32_e32 v37, 10, v37
	v_and_b32_e32 v36, 32, v36
	v_bitop3_b32 v130, v38, v37, v36 bitop3:0xde
	v_mul_f32_e32 v224, 0xbfb8aa3b, v136
	v_mul_f32_e32 v225, v136, v136
	v_pk_mul_f32 v[234:235], v[28:29], v[224:225] op_sel_hi:[1,0]
	v_pk_mul_f32 v[236:237], v[30:31], v[224:225] op_sel_hi:[1,0]
	v_pk_mul_f32 v[238:239], v[20:21], v[224:225] op_sel_hi:[1,0]
	v_pk_mul_f32 v[240:241], v[22:23], v[224:225] op_sel_hi:[1,0]
	v_pk_mul_f32 v[226:227], v[28:29], v[24:25]
	v_pk_mul_f32 v[228:229], v[30:31], v[26:27]
	v_pk_mul_f32 v[230:231], v[20:21], v[16:17]
	v_pk_mul_f32 v[232:233], v[22:23], v[18:19]
	v_exp_f32_e32 v234, v234
	v_exp_f32_e32 v235, v235
	v_exp_f32_e32 v236, v236
	v_exp_f32_e32 v237, v237
	v_exp_f32_e32 v238, v238
	v_exp_f32_e32 v239, v239
	v_exp_f32_e32 v240, v240
	v_exp_f32_e32 v241, v241
	v_pk_mul_f32 v[226:227], v[226:227], v[224:225] op_sel:[0,1] op_sel_hi:[1,1]
	v_pk_mul_f32 v[228:229], v[228:229], v[224:225] op_sel:[0,1] op_sel_hi:[1,1]
	v_pk_mul_f32 v[230:231], v[230:231], v[224:225] op_sel:[0,1] op_sel_hi:[1,1]
	v_pk_mul_f32 v[232:233], v[232:233], v[224:225] op_sel:[0,1] op_sel_hi:[1,1]
	v_pk_add_f32 v[234:235], v[234:235], 1.0 op_sel_hi:[1,0]
	v_pk_add_f32 v[236:237], v[236:237], 1.0 op_sel_hi:[1,0]
	v_pk_add_f32 v[238:239], v[238:239], 1.0 op_sel_hi:[1,0]
	v_pk_add_f32 v[240:241], v[240:241], 1.0 op_sel_hi:[1,0]
	v_rcp_f32_e32 v234, v234
	v_rcp_f32_e32 v235, v235
	v_rcp_f32_e32 v236, v236
	v_rcp_f32_e32 v237, v237
	v_rcp_f32_e32 v238, v238
	v_rcp_f32_e32 v239, v239
	v_rcp_f32_e32 v240, v240
	v_rcp_f32_e32 v241, v241
	v_pk_mul_f32 v[226:227], v[226:227], v[234:235]
	v_pk_mul_f32 v[228:229], v[228:229], v[236:237]
	v_pk_mul_f32 v[230:231], v[230:231], v[238:239]
	v_pk_mul_f32 v[232:233], v[232:233], v[240:241]
	v_cvt_pk_bf16_f32 v242, v226, v227
	v_cvt_pk_bf16_f32 v243, v228, v229
	v_cvt_pk_bf16_f32 v244, v230, v231
	v_cvt_pk_bf16_f32 v245, v232, v233
	v_lshl_add_u64 v[28:29], v[48:49], 0, v[130:131]
	global_store_dwordx4 v[28:29], v[250:253], off
	v_add_u32_e32 v20, 0xa0, v151
	v_lshrrev_b32_e32 v21, 3, v20
	v_and_or_b32 v21, v21, 12, s65
	v_lshlrev_b32_e32 v22, 6, v20
	v_lshlrev_b32_e32 v20, 2, v20
	v_and_or_b32 v22, v22, s64, v143
	v_lshlrev_b32_e32 v21, 10, v21
	v_and_b32_e32 v20, 32, v20
	v_bitop3_b32 v130, v22, v21, v20 bitop3:0xde
	v_lshl_add_u64 v[22:23], v[48:49], 0, v[130:131]
	global_store_dwordx4 v[22:23], v[242:245], off
	v_mul_f32_e32 v224, 0xbfb8aa3b, v137
	v_mul_f32_e32 v225, v137, v137
	v_pk_mul_f32 v[234:235], v[12:13], v[224:225] op_sel_hi:[1,0]
	v_pk_mul_f32 v[236:237], v[14:15], v[224:225] op_sel_hi:[1,0]
	v_pk_mul_f32 v[238:239], v[4:5], v[224:225] op_sel_hi:[1,0]
	v_pk_mul_f32 v[240:241], v[6:7], v[224:225] op_sel_hi:[1,0]
	v_pk_mul_f32 v[226:227], v[12:13], v[8:9]
	v_pk_mul_f32 v[228:229], v[14:15], v[10:11]
	v_pk_mul_f32 v[230:231], v[4:5], v[0:1]
	v_pk_mul_f32 v[232:233], v[6:7], v[2:3]
	v_exp_f32_e32 v234, v234
	v_exp_f32_e32 v235, v235
	v_exp_f32_e32 v236, v236
	v_exp_f32_e32 v237, v237
	v_exp_f32_e32 v238, v238
	v_exp_f32_e32 v239, v239
	v_exp_f32_e32 v240, v240
	v_exp_f32_e32 v241, v241
	v_pk_mul_f32 v[226:227], v[226:227], v[224:225] op_sel:[0,1] op_sel_hi:[1,1]
	v_pk_mul_f32 v[228:229], v[228:229], v[224:225] op_sel:[0,1] op_sel_hi:[1,1]
	v_pk_mul_f32 v[230:231], v[230:231], v[224:225] op_sel:[0,1] op_sel_hi:[1,1]
	v_pk_mul_f32 v[232:233], v[232:233], v[224:225] op_sel:[0,1] op_sel_hi:[1,1]
	v_pk_add_f32 v[234:235], v[234:235], 1.0 op_sel_hi:[1,0]
	v_pk_add_f32 v[236:237], v[236:237], 1.0 op_sel_hi:[1,0]
	v_pk_add_f32 v[238:239], v[238:239], 1.0 op_sel_hi:[1,0]
	v_pk_add_f32 v[240:241], v[240:241], 1.0 op_sel_hi:[1,0]
	v_rcp_f32_e32 v234, v234
	v_rcp_f32_e32 v235, v235
	v_rcp_f32_e32 v236, v236
	v_rcp_f32_e32 v237, v237
	v_rcp_f32_e32 v238, v238
	v_rcp_f32_e32 v239, v239
	v_rcp_f32_e32 v240, v240
	v_rcp_f32_e32 v241, v241
	v_pk_mul_f32 v[226:227], v[226:227], v[234:235]
	v_pk_mul_f32 v[228:229], v[228:229], v[236:237]
	v_pk_mul_f32 v[230:231], v[230:231], v[238:239]
	v_pk_mul_f32 v[232:233], v[232:233], v[240:241]
	v_cvt_pk_bf16_f32 v246, v226, v227
	v_cvt_pk_bf16_f32 v247, v228, v229
	v_cvt_pk_bf16_f32 v248, v230, v231
	v_cvt_pk_bf16_f32 v249, v232, v233
	v_add_u32_e32 v4, 0xb0, v151
	v_lshrrev_b32_e32 v5, 3, v4
	v_and_or_b32 v5, v5, 14, s65
	v_lshlrev_b32_e32 v6, 6, v4
	v_lshlrev_b32_e32 v4, 2, v4
	v_and_or_b32 v6, v6, s64, v143
	v_lshlrev_b32_e32 v5, 10, v5
	v_and_b32_e32 v4, 32, v4
	v_bitop3_b32 v130, v6, v5, v4 bitop3:0xde
	v_lshl_add_u64 v[4:5], v[48:49], 0, v[130:131]
	global_store_dwordx4 v[4:5], v[246:249], off
	s_cbranch_vccnz .LBB0_1621
	s_and_saveexec_b64 s[4:5], s[2:3]
	s_cbranch_execz .LBB0_1631
	v_lshl_or_b32 v0, s46, 8, v208
	v_ashrrev_i32_e32 v1, 31, v0
	v_lshlrev_b64 v[0:1], 6, v[0:1]
	v_lshl_add_u64 v[12:13], s[10:11], 0, v[0:1]
	global_load_dwordx4 v[0:3], v[12:13], off
	global_load_dwordx4 v[4:7], v[12:13], off offset:16
	global_load_dwordx4 v[8:11], v[12:13], off offset:32
	s_nop 0
	global_load_dwordx4 v[12:15], v[12:13], off offset:48
	s_lshl_b32 s45, s72, 10
	s_and_b32 s45, s45, 0x400
	s_waitcnt vmcnt(0)
	v_pk_add_f32 v[2:3], v[2:3], v[6:7]
	v_pk_add_f32 v[0:1], v[0:1], v[4:5]
	v_pk_add_f32 v[4:5], v[10:11], v[14:15]
	v_pk_add_f32 v[6:7], v[8:9], v[12:13]
	v_pk_add_f32 v[2:3], v[2:3], v[4:5]
	v_pk_add_f32 v[0:1], v[0:1], v[6:7]
	s_nop 0
	v_pk_mov_b32 v[4:5], v[0:1], v[2:3] op_sel:[1,0]
	v_mov_b32_e32 v1, v3
	v_pk_add_f32 v[0:1], v[4:5], v[0:1]
	s_nop 0
	v_add_f32_e32 v0, v0, v1
	v_fmamk_f32 v0, v0, 0x3a800000, v150
	v_rsq_f32_e32 v0, v0
	v_add_u32_e32 v1, s45, v145
	ds_write_b32 v1, v0
